# g1t
# speedup vs baseline: 1.0556x; 1.0103x over previous
; __device__ __forceinline__ unsigned pk2(float lo, float hi) { const f32x2_t v = {lo, hi}; const bf16x2_t b = __builtin_convertvector(v, bf16x2_t); return __builtin_bit_cast(unsigned, b); }
;     __device__ __forceinline__ void operator()(const f32x4 (&acc)[2][2][4][2], const Unit& u, int wr, int wc, int fr, int fq) const {
;         const int row0 = u.pm * BM + wr * 64 + fr, col0 = u.pn * BM + wc * 32 + 8 * fq;
; #pragma unroll
;         for (int ai = 0; ai < 2; ++ai)
; #pragma unroll
;             for (int m = 0; m < 4; ++m) { bf16* rowp = O + (size_t)(row0 + ai * HALF + m * 16) * ldc + col0;
; #pragma unroll
;                 for (int bj = 0; bj < 2; ++bj) { const f32x4 v0 = acc[ai][bj][m][0], v1 = acc[ai][bj][m][1];
;                     u32x4 w; w.x = pk2(v0[0], v0[1]); w.y = pk2(v0[2], v0[3]); w.z = pk2(v1[0], v1[1]); w.w = pk2(v1[2], v1[3]);
;                     *(u32x4*)(rowp + bj * HALF) = w; } }
;     }
.LBB0_352:
	v_and_b32_e32 v168, 63, v199
	v_bfe_u32 v169, v199, 4, 2
	v_lshlrev_b32_e32 v169, 2, v169
	v_xor_b32_e32 v169, v168, v169
	v_and_b32_e32 v170, 0x1c0, v199
	v_add_u32_e32 v173, 64, v170
	v_and_b32_e32 v173, 0x200, v173
	v_lshl_add_u32 v170, v170, 4, v173
	v_bfe_u32 v173, v199, 8, 1
	v_mul_u32_u24_e32 v173, 0x1400, v173
	v_add_u32_e32 v170, v170, v173
	v_add_u32_e32 v170, 0x20000, v170
	v_lshl_add_u32 v174, v169, 4, v170
	v_lshrrev_b32_e32 v171, 2, v168
	v_and_b32_e32 v172, 3, v168
	v_lshlrev_b32_e32 v173, 2, v172
	v_xor_b32_e32 v171, v171, v173
	v_lshl_or_b32 v171, v172, 4, v171
	v_lshl_add_u32 v175, v171, 4, v170
	ds_write_b128 v174, v[0:3]
	ds_read_b128 v[0:3], v175
	ds_write_b128 v174, v[4:7]
	ds_read_b128 v[4:7], v175
	ds_write_b128 v174, v[8:11]
	ds_read_b128 v[8:11], v175
	ds_write_b128 v174, v[12:15]
	ds_read_b128 v[12:15], v175
	ds_write_b128 v174, v[16:19]
	ds_read_b128 v[16:19], v175
	ds_write_b128 v174, v[20:23]
	ds_read_b128 v[20:23], v175
	ds_write_b128 v174, v[24:27]
	ds_read_b128 v[24:27], v175
	ds_write_b128 v174, v[28:31]
	ds_read_b128 v[28:31], v175
	ds_write_b128 v174, v[32:35]
	ds_read_b128 v[32:35], v175
	ds_write_b128 v174, v[36:39]
	ds_read_b128 v[36:39], v175
	ds_write_b128 v174, v[40:43]
	ds_read_b128 v[40:43], v175
	ds_write_b128 v174, v[44:47]
	ds_read_b128 v[44:47], v175
	ds_write_b128 v174, v[48:51]
	ds_read_b128 v[48:51], v175
	ds_write_b128 v174, v[52:55]
	ds_read_b128 v[52:55], v175
	ds_write_b128 v174, v[56:59]
	ds_read_b128 v[56:59], v175
	ds_write_b128 v174, v[60:63]
	ds_read_b128 v[60:63], v175
	ds_write_b128 v174, v[64:67]
	ds_read_b128 v[64:67], v175
	ds_write_b128 v174, v[68:71]
	ds_read_b128 v[68:71], v175
	ds_write_b128 v174, v[72:75]
	ds_read_b128 v[72:75], v175
	ds_write_b128 v174, v[76:79]
	ds_read_b128 v[76:79], v175
	ds_write_b128 v174, v[80:83]
	ds_read_b128 v[80:83], v175
	ds_write_b128 v174, v[84:87]
	ds_read_b128 v[84:87], v175
	ds_write_b128 v174, v[88:91]
	ds_read_b128 v[88:91], v175
	ds_write_b128 v174, v[92:95]
	ds_read_b128 v[92:95], v175
	ds_write_b128 v174, v[96:99]
	ds_read_b128 v[96:99], v175
	ds_write_b128 v174, v[100:103]
	ds_read_b128 v[100:103], v175
	ds_write_b128 v174, v[104:107]
	ds_read_b128 v[104:107], v175
	ds_write_b128 v174, v[108:111]
	ds_read_b128 v[108:111], v175
	ds_write_b128 v174, v[112:115]
	ds_read_b128 v[112:115], v175
	ds_write_b128 v174, v[116:119]
	ds_read_b128 v[116:119], v175
	ds_write_b128 v174, v[120:123]
	ds_read_b128 v[120:123], v175
	ds_write_b128 v174, v[124:127]
	ds_read_b128 v[124:127], v175
	s_waitcnt lgkmcnt(0)
	v_mov_b32_e32 v140, v199
	s_lshl_b32 s7, s31, 8
	s_add_i32 s7, s7, s25
	v_bfe_u32 v146, v140, 2, 4
	v_or_b32_e32 v146, s7, v146
	s_lshl_b32 s7, s30, 8
	v_lshlrev_b32_e32 v140, 3, v140
	v_and_or_b32 v140, v140, 24, s7
	v_or_b32_e32 v140, s26, v140
	v_ashrrev_i32_e32 v141, 31, v140
	v_mov_b64_e32 v[142:143], s[52:53]
	v_cvt_pk_bf16_f32 v68, v68, v69
	v_cvt_pk_bf16_f32 v69, v70, v71
	v_cvt_pk_bf16_f32 v70, v64, v65
	v_add_u32_e32 v64, 0x80, v146
	v_mad_i64_i32 v[144:145], s[14:15], v146, s69, v[142:143]
	v_lshlrev_b64 v[140:141], 1, v[140:141]
	v_cvt_pk_bf16_f32 v108, v108, v109
	v_cvt_pk_bf16_f32 v109, v110, v111
	v_cvt_pk_bf16_f32 v110, v104, v105
	v_or_b32_e32 v104, 16, v146
	v_mad_i64_i32 v[64:65], s[14:15], v64, s69, v[142:143]
	v_cvt_pk_bf16_f32 v44, v44, v45
	v_cvt_pk_bf16_f32 v45, v46, v47
	v_cvt_pk_bf16_f32 v46, v40, v41
	v_add_u32_e32 v40, 0x90, v146
	v_lshl_add_u64 v[144:145], v[144:145], 0, v[140:141]
	v_cvt_pk_bf16_f32 v111, v106, v107
	v_mad_i64_i32 v[104:105], s[14:15], v104, s69, v[142:143]
	v_cvt_pk_bf16_f32 v92, v92, v93
	v_cvt_pk_bf16_f32 v93, v94, v95
	v_cvt_pk_bf16_f32 v94, v88, v89
	v_or_b32_e32 v88, 32, v146
	v_lshl_add_u64 v[64:65], v[64:65], 0, v[140:141]
	v_cvt_pk_bf16_f32 v47, v42, v43
	v_mad_i64_i32 v[40:41], s[14:15], v40, s69, v[142:143]
	v_cvt_pk_bf16_f32 v28, v28, v29
	v_cvt_pk_bf16_f32 v29, v30, v31
	v_cvt_pk_bf16_f32 v30, v24, v25
	v_add_u32_e32 v24, 0xa0, v146
	global_store_dwordx4 v[144:145], v[108:111], off offset:256
	v_cvt_pk_bf16_f32 v95, v90, v91
	v_mad_i64_i32 v[88:89], s[14:15], v88, s69, v[142:143]
	v_lshl_add_u64 v[108:109], v[104:105], 0, v[140:141]
	v_cvt_pk_bf16_f32 v76, v76, v77
	v_cvt_pk_bf16_f32 v77, v78, v79
	v_cvt_pk_bf16_f32 v78, v72, v73
	v_or_b32_e32 v72, 48, v146
	global_store_dwordx4 v[64:65], v[44:47], off offset:256
	v_cvt_pk_bf16_f32 v31, v26, v27
	v_mad_i64_i32 v[24:25], s[14:15], v24, s69, v[142:143]
	v_lshl_add_u64 v[44:45], v[40:41], 0, v[140:141]
	v_cvt_pk_bf16_f32 v12, v12, v13
	v_cvt_pk_bf16_f32 v13, v14, v15
	v_cvt_pk_bf16_f32 v14, v8, v9
	v_add_u32_e32 v8, 0xb0, v146
	global_store_dwordx4 v[108:109], v[92:95], off offset:256
	v_cvt_pk_bf16_f32 v79, v74, v75
	v_mad_i64_i32 v[72:73], s[14:15], v72, s69, v[142:143]
	v_lshl_add_u64 v[92:93], v[88:89], 0, v[140:141]
	global_store_dwordx4 v[44:45], v[28:31], off offset:256
	v_cvt_pk_bf16_f32 v15, v10, v11
	v_mad_i64_i32 v[8:9], s[14:15], v8, s69, v[142:143]
	v_lshl_add_u64 v[28:29], v[24:25], 0, v[140:141]
	v_cvt_pk_bf16_f32 v124, v124, v125
	v_cvt_pk_bf16_f32 v125, v126, v127
	v_cvt_pk_bf16_f32 v126, v120, v121
	v_cvt_pk_bf16_f32 v127, v122, v123
	v_cvt_pk_bf16_f32 v104, v116, v117
	v_cvt_pk_bf16_f32 v105, v118, v119
	v_cvt_pk_bf16_f32 v106, v112, v113
	v_cvt_pk_bf16_f32 v107, v114, v115
	v_cvt_pk_bf16_f32 v88, v100, v101
	v_cvt_pk_bf16_f32 v89, v102, v103
	v_cvt_pk_bf16_f32 v90, v96, v97
	v_cvt_pk_bf16_f32 v91, v98, v99
	global_store_dwordx4 v[92:93], v[76:79], off offset:256
	v_cvt_pk_bf16_f32 v74, v80, v81
	v_cvt_pk_bf16_f32 v75, v82, v83
	v_lshl_add_u64 v[76:77], v[72:73], 0, v[140:141]
	v_cvt_pk_bf16_f32 v72, v84, v85
	v_cvt_pk_bf16_f32 v73, v86, v87
	v_cvt_pk_bf16_f32 v71, v66, v67
	v_cvt_pk_bf16_f32 v60, v60, v61
	v_cvt_pk_bf16_f32 v61, v62, v63
	v_cvt_pk_bf16_f32 v62, v56, v57
	v_cvt_pk_bf16_f32 v63, v58, v59
	v_cvt_pk_bf16_f32 v40, v52, v53
	v_cvt_pk_bf16_f32 v41, v54, v55
	v_cvt_pk_bf16_f32 v42, v48, v49
	v_cvt_pk_bf16_f32 v43, v50, v51
	v_cvt_pk_bf16_f32 v24, v36, v37
	v_cvt_pk_bf16_f32 v25, v38, v39
	v_cvt_pk_bf16_f32 v26, v32, v33
	v_cvt_pk_bf16_f32 v27, v34, v35
	global_store_dwordx4 v[28:29], v[12:15], off offset:256
	v_cvt_pk_bf16_f32 v10, v16, v17
	v_cvt_pk_bf16_f32 v11, v18, v19
	v_lshl_add_u64 v[12:13], v[8:9], 0, v[140:141]
	v_cvt_pk_bf16_f32 v8, v20, v21
	v_cvt_pk_bf16_f32 v9, v22, v23
	v_cvt_pk_bf16_f32 v4, v4, v5
	v_cvt_pk_bf16_f32 v5, v6, v7
	v_cvt_pk_bf16_f32 v6, v0, v1
	v_cvt_pk_bf16_f32 v7, v2, v3
	s_andn2_b64 vcc, exec, s[4:5]
	s_mov_b64 s[4:5], -1
	global_store_dwordx4 v[144:145], v[124:127], off
	global_store_dwordx4 v[108:109], v[104:107], off
	global_store_dwordx4 v[92:93], v[88:91], off
	global_store_dwordx4 v[76:77], v[72:75], off
	global_store_dwordx4 v[76:77], v[68:71], off offset:256
	global_store_dwordx4 v[64:65], v[60:63], off
	global_store_dwordx4 v[44:45], v[40:43], off
	global_store_dwordx4 v[28:29], v[24:27], off
	global_store_dwordx4 v[12:13], v[8:11], off
	global_store_dwordx4 v[12:13], v[4:7], off offset:256
	s_cbranch_vccnz .LBB0_345
; #define PG8_BAR __builtin_amdgcn_s_barrier()
; template <class Epi, int N_, int K_, int LDA_>
; __device__ __forceinline__ void gemm_phase(LAS unsigned char* lds, const Gemm g, const Epi& E) {
;     ...
;         if (!has_next) break;
; #pragma unroll
;         for (int a = 0; a < 2; ++a)
; #pragma unroll
;             for (int b = 0; b < 2; ++b)
; #pragma unroll
;                 for (int m = 0; m < 4; ++m)
; #pragma unroll
;                     for (int n = 0; n < 2; ++n) acc[a][b][m][n] = (f32x4){0.f, 0.f, 0.f, 0.f};
;         cur = nxt; cA = nA; cB = nB; ++ui;
;         if (wr == 1) PG8_BAR;
	s_andn2_b64 vcc, exec, s[0:1]
	s_cbranch_vccnz .LBB0_344
	s_barrier
	s_branch .LBB0_344

; __device__ __forceinline__ unsigned pk2(float lo, float hi) { const f32x2_t v = {lo, hi}; const bf16x2_t b = __builtin_convertvector(v, bf16x2_t); return __builtin_bit_cast(unsigned, b); }
;     __device__ __forceinline__ void operator()(const f32x4 (&acc)[2][2][4][2], const Unit& u, int wr, int wc, int fr, int fq) const {
;         const int row0 = u.pm * BM + wr * 64 + fr, col0 = u.pn * BM + wc * 32 + 8 * fq;
; #pragma unroll
;         for (int ai = 0; ai < 2; ++ai)
; #pragma unroll
;             for (int m = 0; m < 4; ++m) { bf16* rowp = O + (size_t)(row0 + ai * HALF + m * 16) * ldc + col0;
; #pragma unroll
;                 for (int bj = 0; bj < 2; ++bj) { const f32x4 v0 = acc[ai][bj][m][0], v1 = acc[ai][bj][m][1];
;                     u32x4 w; w.x = pk2(v0[0], v0[1]); w.y = pk2(v0[2], v0[3]); w.z = pk2(v1[0], v1[1]); w.w = pk2(v1[2], v1[3]);
;                     *(u32x4*)(rowp + bj * HALF) = w; } }
;     }
.LBB0_370:
	v_and_b32_e32 v168, 63, v199
	v_bfe_u32 v169, v199, 4, 2
	v_lshlrev_b32_e32 v169, 2, v169
	v_xor_b32_e32 v169, v168, v169
	v_and_b32_e32 v170, 0x1c0, v199
	v_add_u32_e32 v173, 64, v170
	v_and_b32_e32 v173, 0x200, v173
	v_lshl_add_u32 v170, v170, 4, v173
	v_bfe_u32 v173, v199, 8, 1
	v_mul_u32_u24_e32 v173, 0x1400, v173
	v_add_u32_e32 v170, v170, v173
	v_add_u32_e32 v170, 0x20000, v170
	v_lshl_add_u32 v174, v169, 4, v170
	v_lshrrev_b32_e32 v171, 2, v168
	v_and_b32_e32 v172, 3, v168
	v_lshlrev_b32_e32 v173, 2, v172
	v_xor_b32_e32 v171, v171, v173
	v_lshl_or_b32 v171, v172, 4, v171
	v_lshl_add_u32 v175, v171, 4, v170
	ds_write_b128 v174, v[0:3]
	ds_read_b128 v[0:3], v175
	ds_write_b128 v174, v[4:7]
	ds_read_b128 v[4:7], v175
	ds_write_b128 v174, v[8:11]
	ds_read_b128 v[8:11], v175
	ds_write_b128 v174, v[12:15]
	ds_read_b128 v[12:15], v175
	ds_write_b128 v174, v[16:19]
	ds_read_b128 v[16:19], v175
	ds_write_b128 v174, v[20:23]
	ds_read_b128 v[20:23], v175
	ds_write_b128 v174, v[24:27]
	ds_read_b128 v[24:27], v175
	ds_write_b128 v174, v[28:31]
	ds_read_b128 v[28:31], v175
	ds_write_b128 v174, v[32:35]
	ds_read_b128 v[32:35], v175
	ds_write_b128 v174, v[36:39]
	ds_read_b128 v[36:39], v175
	ds_write_b128 v174, v[40:43]
	ds_read_b128 v[40:43], v175
	ds_write_b128 v174, v[44:47]
	ds_read_b128 v[44:47], v175
	ds_write_b128 v174, v[48:51]
	ds_read_b128 v[48:51], v175
	ds_write_b128 v174, v[52:55]
	ds_read_b128 v[52:55], v175
	ds_write_b128 v174, v[56:59]
	ds_read_b128 v[56:59], v175
	ds_write_b128 v174, v[60:63]
	ds_read_b128 v[60:63], v175
	ds_write_b128 v174, v[64:67]
	ds_read_b128 v[64:67], v175
	ds_write_b128 v174, v[68:71]
	ds_read_b128 v[68:71], v175
	ds_write_b128 v174, v[72:75]
	ds_read_b128 v[72:75], v175
	ds_write_b128 v174, v[76:79]
	ds_read_b128 v[76:79], v175
	ds_write_b128 v174, v[80:83]
	ds_read_b128 v[80:83], v175
	ds_write_b128 v174, v[84:87]
	ds_read_b128 v[84:87], v175
	ds_write_b128 v174, v[88:91]
	ds_read_b128 v[88:91], v175
	ds_write_b128 v174, v[92:95]
	ds_read_b128 v[92:95], v175
	ds_write_b128 v174, v[96:99]
	ds_read_b128 v[96:99], v175
	ds_write_b128 v174, v[100:103]
	ds_read_b128 v[100:103], v175
	ds_write_b128 v174, v[104:107]
	ds_read_b128 v[104:107], v175
	ds_write_b128 v174, v[108:111]
	ds_read_b128 v[108:111], v175
	ds_write_b128 v174, v[112:115]
	ds_read_b128 v[112:115], v175
	ds_write_b128 v174, v[116:119]
	ds_read_b128 v[116:119], v175
	ds_write_b128 v174, v[120:123]
	ds_read_b128 v[120:123], v175
	ds_write_b128 v174, v[124:127]
	ds_read_b128 v[124:127], v175
	s_waitcnt lgkmcnt(0)
	v_mov_b32_e32 v140, v199
	s_lshl_b32 s7, s31, 8
	s_add_i32 s7, s7, s25
	v_bfe_u32 v146, v140, 2, 4
	v_or_b32_e32 v146, s7, v146
	s_lshl_b32 s7, s30, 8
	v_lshlrev_b32_e32 v140, 3, v140
	v_and_or_b32 v140, v140, 24, s7
	v_or_b32_e32 v140, s26, v140
	v_ashrrev_i32_e32 v141, 31, v140
	v_mov_b64_e32 v[142:143], s[52:53]
	v_cvt_pk_bf16_f32 v68, v68, v69
	v_cvt_pk_bf16_f32 v69, v70, v71
	v_cvt_pk_bf16_f32 v70, v64, v65
	v_add_u32_e32 v64, 0x80, v146
	v_mad_i64_i32 v[144:145], s[14:15], v146, s70, v[142:143]
	v_lshlrev_b64 v[140:141], 1, v[140:141]
	v_cvt_pk_bf16_f32 v108, v108, v109
	v_cvt_pk_bf16_f32 v109, v110, v111
	v_cvt_pk_bf16_f32 v110, v104, v105
	v_or_b32_e32 v104, 16, v146
	v_mad_i64_i32 v[64:65], s[14:15], v64, s70, v[142:143]
	v_cvt_pk_bf16_f32 v44, v44, v45
	v_cvt_pk_bf16_f32 v45, v46, v47
	v_cvt_pk_bf16_f32 v46, v40, v41
	v_add_u32_e32 v40, 0x90, v146
	v_lshl_add_u64 v[144:145], v[144:145], 0, v[140:141]
	v_cvt_pk_bf16_f32 v111, v106, v107
	v_mad_i64_i32 v[104:105], s[14:15], v104, s70, v[142:143]
	v_cvt_pk_bf16_f32 v92, v92, v93
	v_cvt_pk_bf16_f32 v93, v94, v95
	v_cvt_pk_bf16_f32 v94, v88, v89
	v_or_b32_e32 v88, 32, v146
	v_lshl_add_u64 v[64:65], v[64:65], 0, v[140:141]
	v_cvt_pk_bf16_f32 v47, v42, v43
	v_mad_i64_i32 v[40:41], s[14:15], v40, s70, v[142:143]
	v_cvt_pk_bf16_f32 v28, v28, v29
	v_cvt_pk_bf16_f32 v29, v30, v31
	v_cvt_pk_bf16_f32 v30, v24, v25
	v_add_u32_e32 v24, 0xa0, v146
	global_store_dwordx4 v[144:145], v[108:111], off offset:256
	v_cvt_pk_bf16_f32 v95, v90, v91
	v_mad_i64_i32 v[88:89], s[14:15], v88, s70, v[142:143]
	v_lshl_add_u64 v[108:109], v[104:105], 0, v[140:141]
	v_cvt_pk_bf16_f32 v76, v76, v77
	v_cvt_pk_bf16_f32 v77, v78, v79
	v_cvt_pk_bf16_f32 v78, v72, v73
	v_or_b32_e32 v72, 48, v146
	global_store_dwordx4 v[64:65], v[44:47], off offset:256
	v_cvt_pk_bf16_f32 v31, v26, v27
	v_mad_i64_i32 v[24:25], s[14:15], v24, s70, v[142:143]
	v_lshl_add_u64 v[44:45], v[40:41], 0, v[140:141]
	v_cvt_pk_bf16_f32 v12, v12, v13
	v_cvt_pk_bf16_f32 v13, v14, v15
	v_cvt_pk_bf16_f32 v14, v8, v9
	v_add_u32_e32 v8, 0xb0, v146
	global_store_dwordx4 v[108:109], v[92:95], off offset:256
	v_cvt_pk_bf16_f32 v79, v74, v75
	v_mad_i64_i32 v[72:73], s[14:15], v72, s70, v[142:143]
	v_lshl_add_u64 v[92:93], v[88:89], 0, v[140:141]
	global_store_dwordx4 v[44:45], v[28:31], off offset:256
	v_cvt_pk_bf16_f32 v15, v10, v11
	v_mad_i64_i32 v[8:9], s[14:15], v8, s70, v[142:143]
	v_lshl_add_u64 v[28:29], v[24:25], 0, v[140:141]
	v_cvt_pk_bf16_f32 v124, v124, v125
	v_cvt_pk_bf16_f32 v125, v126, v127
	v_cvt_pk_bf16_f32 v126, v120, v121
	v_cvt_pk_bf16_f32 v127, v122, v123
	v_cvt_pk_bf16_f32 v104, v116, v117
	v_cvt_pk_bf16_f32 v105, v118, v119
	v_cvt_pk_bf16_f32 v106, v112, v113
	v_cvt_pk_bf16_f32 v107, v114, v115
	v_cvt_pk_bf16_f32 v88, v100, v101
	v_cvt_pk_bf16_f32 v89, v102, v103
	v_cvt_pk_bf16_f32 v90, v96, v97
	v_cvt_pk_bf16_f32 v91, v98, v99
	global_store_dwordx4 v[92:93], v[76:79], off offset:256
	v_cvt_pk_bf16_f32 v74, v80, v81
	v_cvt_pk_bf16_f32 v75, v82, v83
	v_lshl_add_u64 v[76:77], v[72:73], 0, v[140:141]
	v_cvt_pk_bf16_f32 v72, v84, v85
	v_cvt_pk_bf16_f32 v73, v86, v87
	v_cvt_pk_bf16_f32 v71, v66, v67
	v_cvt_pk_bf16_f32 v60, v60, v61
	v_cvt_pk_bf16_f32 v61, v62, v63
	v_cvt_pk_bf16_f32 v62, v56, v57
	v_cvt_pk_bf16_f32 v63, v58, v59
	v_cvt_pk_bf16_f32 v40, v52, v53
	v_cvt_pk_bf16_f32 v41, v54, v55
	v_cvt_pk_bf16_f32 v42, v48, v49
	v_cvt_pk_bf16_f32 v43, v50, v51
	v_cvt_pk_bf16_f32 v24, v36, v37
	v_cvt_pk_bf16_f32 v25, v38, v39
	v_cvt_pk_bf16_f32 v26, v32, v33
	v_cvt_pk_bf16_f32 v27, v34, v35
	global_store_dwordx4 v[28:29], v[12:15], off offset:256
	v_cvt_pk_bf16_f32 v10, v16, v17
	v_cvt_pk_bf16_f32 v11, v18, v19
	v_lshl_add_u64 v[12:13], v[8:9], 0, v[140:141]
	v_cvt_pk_bf16_f32 v8, v20, v21
	v_cvt_pk_bf16_f32 v9, v22, v23
	v_cvt_pk_bf16_f32 v4, v4, v5
	v_cvt_pk_bf16_f32 v5, v6, v7
	v_cvt_pk_bf16_f32 v6, v0, v1
	v_cvt_pk_bf16_f32 v7, v2, v3
	s_andn2_b64 vcc, exec, s[4:5]
	s_mov_b64 s[4:5], -1
	global_store_dwordx4 v[144:145], v[124:127], off
	global_store_dwordx4 v[108:109], v[104:107], off
	global_store_dwordx4 v[92:93], v[88:91], off
	global_store_dwordx4 v[76:77], v[72:75], off
	global_store_dwordx4 v[76:77], v[68:71], off offset:256
	global_store_dwordx4 v[64:65], v[60:63], off
	global_store_dwordx4 v[44:45], v[40:43], off
	global_store_dwordx4 v[28:29], v[24:27], off
	global_store_dwordx4 v[12:13], v[8:11], off
	global_store_dwordx4 v[12:13], v[4:7], off offset:256
	s_cbranch_vccnz .LBB0_363
; #define PG8_BAR __builtin_amdgcn_s_barrier()
; template <class Epi, int N_, int K_, int LDA_>
; __device__ __forceinline__ void gemm_phase(LAS unsigned char* lds, const Gemm g, const Epi& E) {
;     ...
;         if (!has_next) break;
; #pragma unroll
;         for (int a = 0; a < 2; ++a)
; #pragma unroll
;             for (int b = 0; b < 2; ++b)
; #pragma unroll
;                 for (int m = 0; m < 4; ++m)
; #pragma unroll
;                     for (int n = 0; n < 2; ++n) acc[a][b][m][n] = (f32x4){0.f, 0.f, 0.f, 0.f};
;         cur = nxt; cA = nA; cB = nB; ++ui;
;         if (wr == 1) PG8_BAR;
	s_andn2_b64 vcc, exec, s[0:1]
	s_cbranch_vccnz .LBB0_362
	s_barrier
	s_branch .LBB0_362
